# adaLN item of phase 0 rewritten by hand: all conditioning and weight loads issued up front, counted waits
# speedup vs baseline: 1.0052x; 1.0052x over previous
.LBB0_73:
	v_mov_b32_e32 v0, v188
	v_lshlrev_b32_e32 v21, 2, v0
	s_mov_b64 s[10:11], s[42:43]
	global_load_dword v94, v21, s[10:11]
	global_load_dword v95, v21, s[10:11] offset:2048
	s_add_u32 s10, s10, 0x1000
	s_addc_u32 s11, s11, 0
	global_load_dword v96, v21, s[10:11]
	global_load_dword v97, v21, s[10:11] offset:2048
	s_add_u32 s10, s10, 0x1000
	s_addc_u32 s11, s11, 0
	global_load_dword v98, v21, s[10:11]
	global_load_dword v99, v21, s[10:11] offset:2048
	s_add_u32 s10, s10, 0x1000
	s_addc_u32 s11, s11, 0
	global_load_dword v100, v21, s[10:11]
	global_load_dword v101, v21, s[10:11] offset:2048
	global_load_dword v102, v21, s[46:47]
	global_load_dword v103, v21, s[46:47] offset:2048
	v_and_b32_e32 v1, 31, v0
	v_lshrrev_b32_e32 v10, 5, v0
	v_add_u32_e32 v2, s96, v1
	v_lshlrev_b32_e32 v2, 2, v2
	v_mul_u32_u24_e32 v3, 0x180000, v10
	v_add_u32_e32 v3, v3, v2
	s_sub_u32 s8, s26, 0x2a000
	s_subb_u32 s9, s27, 0
	global_load_dword v132, v3, s[8:9]
	s_add_u32 s8, s8, 0x6000
	s_addc_u32 s9, s9, 0
	global_load_dword v133, v3, s[8:9]
	s_add_u32 s8, s8, 0x6000
	s_addc_u32 s9, s9, 0
	global_load_dword v134, v3, s[8:9]
	s_add_u32 s8, s8, 0x6000
	s_addc_u32 s9, s9, 0
	global_load_dword v135, v3, s[8:9]
	s_add_u32 s8, s8, 0x6000
	s_addc_u32 s9, s9, 0
	global_load_dword v136, v3, s[8:9]
	s_add_u32 s8, s8, 0x6000
	s_addc_u32 s9, s9, 0
	global_load_dword v137, v3, s[8:9]
	s_add_u32 s8, s8, 0x6000
	s_addc_u32 s9, s9, 0
	global_load_dword v138, v3, s[8:9]
	s_add_u32 s8, s8, 0x6000
	s_addc_u32 s9, s9, 0
	global_load_dword v139, v3, s[8:9]
	s_add_u32 s8, s8, 0x6000
	s_addc_u32 s9, s9, 0
	global_load_dword v140, v3, s[8:9]
	s_add_u32 s8, s8, 0x6000
	s_addc_u32 s9, s9, 0
	global_load_dword v141, v3, s[8:9]
	s_add_u32 s8, s8, 0x6000
	s_addc_u32 s9, s9, 0
	global_load_dword v142, v3, s[8:9]
	s_add_u32 s8, s8, 0x6000
	s_addc_u32 s9, s9, 0
	global_load_dword v143, v3, s[8:9]
	s_add_u32 s8, s8, 0x6000
	s_addc_u32 s9, s9, 0
	global_load_dword v144, v3, s[8:9]
	s_add_u32 s8, s8, 0x6000
	s_addc_u32 s9, s9, 0
	global_load_dword v145, v3, s[8:9]
	s_add_u32 s8, s8, 0x6000
	s_addc_u32 s9, s9, 0
	global_load_dword v146, v3, s[8:9]
	s_add_u32 s8, s8, 0x6000
	s_addc_u32 s9, s9, 0
	global_load_dword v147, v3, s[8:9]
	s_add_u32 s8, s8, 0x6000
	s_addc_u32 s9, s9, 0
	global_load_dword v148, v3, s[8:9]
	s_add_u32 s8, s8, 0x6000
	s_addc_u32 s9, s9, 0
	global_load_dword v149, v3, s[8:9]
	s_add_u32 s8, s8, 0x6000
	s_addc_u32 s9, s9, 0
	global_load_dword v150, v3, s[8:9]
	s_add_u32 s8, s8, 0x6000
	s_addc_u32 s9, s9, 0
	global_load_dword v151, v3, s[8:9]
	s_add_u32 s8, s8, 0x6000
	s_addc_u32 s9, s9, 0
	global_load_dword v152, v3, s[8:9]
	s_add_u32 s8, s8, 0x6000
	s_addc_u32 s9, s9, 0
	global_load_dword v153, v3, s[8:9]
	s_add_u32 s8, s8, 0x6000
	s_addc_u32 s9, s9, 0
	global_load_dword v154, v3, s[8:9]
	s_add_u32 s8, s8, 0x6000
	s_addc_u32 s9, s9, 0
	global_load_dword v155, v3, s[8:9]
	s_add_u32 s8, s8, 0x6000
	s_addc_u32 s9, s9, 0
	global_load_dword v156, v3, s[8:9]
	s_add_u32 s8, s8, 0x6000
	s_addc_u32 s9, s9, 0
	global_load_dword v157, v3, s[8:9]
	s_add_u32 s8, s8, 0x6000
	s_addc_u32 s9, s9, 0
	global_load_dword v158, v3, s[8:9]
	s_add_u32 s8, s8, 0x6000
	s_addc_u32 s9, s9, 0
	global_load_dword v159, v3, s[8:9]
	s_add_u32 s8, s8, 0x6000
	s_addc_u32 s9, s9, 0
	global_load_dword v160, v3, s[8:9]
	s_add_u32 s8, s8, 0x6000
	s_addc_u32 s9, s9, 0
	global_load_dword v161, v3, s[8:9]
	s_add_u32 s8, s8, 0x6000
	s_addc_u32 s9, s9, 0
	global_load_dword v162, v3, s[8:9]
	s_add_u32 s8, s8, 0x6000
	s_addc_u32 s9, s9, 0
	global_load_dword v163, v3, s[8:9]
	s_add_u32 s8, s8, 0x6000
	s_addc_u32 s9, s9, 0
	s_waitcnt vmcnt(32)
	v_mul_f32_e32 v104, 0xbfb8aa3b, v94
	v_mul_f32_e32 v105, 0xbfb8aa3b, v95
	v_mul_f32_e32 v106, 0xbfb8aa3b, v96
	v_mul_f32_e32 v107, 0xbfb8aa3b, v97
	v_mul_f32_e32 v108, 0xbfb8aa3b, v98
	v_mul_f32_e32 v109, 0xbfb8aa3b, v99
	v_mul_f32_e32 v110, 0xbfb8aa3b, v100
	v_mul_f32_e32 v111, 0xbfb8aa3b, v101
	v_mul_f32_e32 v112, 0xbfb8aa3b, v102
	v_mul_f32_e32 v113, 0xbfb8aa3b, v103
	v_exp_f32_e32 v104, v104
	v_exp_f32_e32 v105, v105
	v_exp_f32_e32 v106, v106
	v_exp_f32_e32 v107, v107
	v_exp_f32_e32 v108, v108
	v_exp_f32_e32 v109, v109
	v_exp_f32_e32 v110, v110
	v_exp_f32_e32 v111, v111
	v_exp_f32_e32 v112, v112
	v_exp_f32_e32 v113, v113
	v_add_f32_e32 v104, 1.0, v104
	v_add_f32_e32 v105, 1.0, v105
	v_add_f32_e32 v106, 1.0, v106
	v_add_f32_e32 v107, 1.0, v107
	v_add_f32_e32 v108, 1.0, v108
	v_add_f32_e32 v109, 1.0, v109
	v_add_f32_e32 v110, 1.0, v110
	v_add_f32_e32 v111, 1.0, v111
	v_add_f32_e32 v112, 1.0, v112
	v_add_f32_e32 v113, 1.0, v113
	v_rcp_f32_e32 v104, v104
	v_rcp_f32_e32 v105, v105
	v_rcp_f32_e32 v106, v106
	v_rcp_f32_e32 v107, v107
	v_rcp_f32_e32 v108, v108
	v_rcp_f32_e32 v109, v109
	v_rcp_f32_e32 v110, v110
	v_rcp_f32_e32 v111, v111
	v_rcp_f32_e32 v112, v112
	v_rcp_f32_e32 v113, v113
	v_mul_f32_e32 v94, v94, v104
	v_mul_f32_e32 v95, v95, v105
	v_mul_f32_e32 v96, v96, v106
	v_mul_f32_e32 v97, v97, v107
	v_mul_f32_e32 v98, v98, v108
	v_mul_f32_e32 v99, v99, v109
	v_mul_f32_e32 v100, v100, v110
	v_mul_f32_e32 v101, v101, v111
	v_mul_f32_e32 v102, v102, v112
	v_mul_f32_e32 v103, v103, v113
	ds_write_b32 v21, v94
	ds_write_b32 v21, v95 offset:2048
	ds_write_b32 v21, v96 offset:4096
	ds_write_b32 v21, v97 offset:6144
	ds_write_b32 v21, v98 offset:8192
	ds_write_b32 v21, v99 offset:10240
	ds_write_b32 v21, v100 offset:12288
	ds_write_b32 v21, v101 offset:14336
	ds_write_b32 v21, v102 offset:16384
	ds_write_b32 v21, v103 offset:18432
	global_load_dword v164, v3, s[8:9]
	s_add_u32 s8, s8, 0x6000
	s_addc_u32 s9, s9, 0
	global_load_dword v165, v3, s[8:9]
	s_add_u32 s8, s8, 0x6000
	s_addc_u32 s9, s9, 0
	global_load_dword v166, v3, s[8:9]
	s_add_u32 s8, s8, 0x6000
	s_addc_u32 s9, s9, 0
	global_load_dword v167, v3, s[8:9]
	s_add_u32 s8, s8, 0x6000
	s_addc_u32 s9, s9, 0
	global_load_dword v168, v3, s[8:9]
	s_add_u32 s8, s8, 0x6000
	s_addc_u32 s9, s9, 0
	global_load_dword v169, v3, s[8:9]
	s_add_u32 s8, s8, 0x6000
	s_addc_u32 s9, s9, 0
	global_load_dword v170, v3, s[8:9]
	s_add_u32 s8, s8, 0x6000
	s_addc_u32 s9, s9, 0
	global_load_dword v171, v3, s[8:9]
	s_add_u32 s8, s8, 0x6000
	s_addc_u32 s9, s9, 0
	global_load_dword v172, v3, s[8:9]
	s_add_u32 s8, s8, 0x6000
	s_addc_u32 s9, s9, 0
	global_load_dword v173, v3, s[8:9]
	s_add_u32 s8, s8, 0x6000
	s_addc_u32 s9, s9, 0
	global_load_dword v174, v3, s[8:9]
	s_add_u32 s8, s8, 0x6000
	s_addc_u32 s9, s9, 0
	global_load_dword v175, v3, s[8:9]
	s_add_u32 s8, s8, 0x6000
	s_addc_u32 s9, s9, 0
	global_load_dword v176, v3, s[8:9]
	s_add_u32 s8, s8, 0x6000
	s_addc_u32 s9, s9, 0
	global_load_dword v177, v3, s[8:9]
	s_add_u32 s8, s8, 0x6000
	s_addc_u32 s9, s9, 0
	global_load_dword v178, v3, s[8:9]
	s_add_u32 s8, s8, 0x6000
	s_addc_u32 s9, s9, 0
	global_load_dword v179, v3, s[8:9]
	s_add_u32 s8, s8, 0x6000
	s_addc_u32 s9, s9, 0
	global_load_dword v180, v3, s[8:9]
	s_add_u32 s8, s8, 0x6000
	s_addc_u32 s9, s9, 0
	global_load_dword v181, v3, s[8:9]
	s_add_u32 s8, s8, 0x6000
	s_addc_u32 s9, s9, 0
	global_load_dword v182, v3, s[8:9]
	s_add_u32 s8, s8, 0x6000
	s_addc_u32 s9, s9, 0
	global_load_dword v183, v3, s[8:9]
	s_add_u32 s8, s8, 0x6000
	s_addc_u32 s9, s9, 0
	global_load_dword v184, v3, s[8:9]
	s_add_u32 s8, s8, 0x6000
	s_addc_u32 s9, s9, 0
	global_load_dword v185, v3, s[8:9]
	s_add_u32 s8, s8, 0x6000
	s_addc_u32 s9, s9, 0
	global_load_dword v186, v3, s[8:9]
	s_add_u32 s8, s8, 0x6000
	s_addc_u32 s9, s9, 0
	global_load_dword v187, v3, s[8:9]
	s_add_u32 s8, s8, 0x6000
	s_addc_u32 s9, s9, 0
	global_load_dword v192, v3, s[8:9]
	s_add_u32 s8, s8, 0x6000
	s_addc_u32 s9, s9, 0
	global_load_dword v193, v3, s[8:9]
	s_add_u32 s8, s8, 0x6000
	s_addc_u32 s9, s9, 0
	global_load_dword v194, v3, s[8:9]
	s_add_u32 s8, s8, 0x6000
	s_addc_u32 s9, s9, 0
	global_load_dword v195, v3, s[8:9]
	s_add_u32 s8, s8, 0x6000
	s_addc_u32 s9, s9, 0
	global_load_dword v196, v3, s[8:9]
	s_add_u32 s8, s8, 0x6000
	s_addc_u32 s9, s9, 0
	global_load_dword v197, v3, s[8:9]
	s_add_u32 s8, s8, 0x6000
	s_addc_u32 s9, s9, 0
	global_load_dword v198, v3, s[8:9]
	s_add_u32 s8, s8, 0x6000
	s_addc_u32 s9, s9, 0
	global_load_dword v199, v3, s[8:9]
	s_add_u32 s8, s8, 0x6000
	s_addc_u32 s9, s9, 0
	v_lshlrev_b32_e32 v23, 8, v10
	s_waitcnt lgkmcnt(0)
	s_barrier
	ds_read_b128 v[28:31], v23
	ds_read_b128 v[32:35], v23 offset:4096
	ds_read_b128 v[36:39], v23 offset:8192
	ds_read_b128 v[40:43], v23 offset:12288
	ds_read_b128 v[44:47], v23 offset:16384
	ds_read_b128 v[74:77], v23 offset:16
	ds_read_b128 v[78:81], v23 offset:4112
	ds_read_b128 v[82:85], v23 offset:8208
	ds_read_b128 v[86:89], v23 offset:12304
	ds_read_b128 v[90:93], v23 offset:16400
	s_waitcnt vmcnt(60) lgkmcnt(5)
	v_mul_f32_e32 v4, v28, v132
	v_mul_f32_e32 v5, v32, v132
	v_mul_f32_e32 v12, v36, v132
	v_mul_f32_e32 v13, v40, v132
	v_mul_f32_e32 v22, v44, v132
	v_fmac_f32_e32 v4, v29, v133
	v_fmac_f32_e32 v5, v33, v133
	v_fmac_f32_e32 v12, v37, v133
	v_fmac_f32_e32 v13, v41, v133
	v_fmac_f32_e32 v22, v45, v133
	v_fmac_f32_e32 v4, v30, v134
	v_fmac_f32_e32 v5, v34, v134
	v_fmac_f32_e32 v12, v38, v134
	v_fmac_f32_e32 v13, v42, v134
	v_fmac_f32_e32 v22, v46, v134
	v_fmac_f32_e32 v4, v31, v135
	v_fmac_f32_e32 v5, v35, v135
	v_fmac_f32_e32 v12, v39, v135
	v_fmac_f32_e32 v13, v43, v135
	v_fmac_f32_e32 v22, v47, v135
	ds_read_b128 v[28:31], v23 offset:32
	ds_read_b128 v[32:35], v23 offset:4128
	ds_read_b128 v[36:39], v23 offset:8224
	ds_read_b128 v[40:43], v23 offset:12320
	ds_read_b128 v[44:47], v23 offset:16416
	s_waitcnt vmcnt(56) lgkmcnt(5)
	v_fmac_f32_e32 v4, v74, v136
	v_fmac_f32_e32 v5, v78, v136
	v_fmac_f32_e32 v12, v82, v136
	v_fmac_f32_e32 v13, v86, v136
	v_fmac_f32_e32 v22, v90, v136
	v_fmac_f32_e32 v4, v75, v137
	v_fmac_f32_e32 v5, v79, v137
	v_fmac_f32_e32 v12, v83, v137
	v_fmac_f32_e32 v13, v87, v137
	v_fmac_f32_e32 v22, v91, v137
	v_fmac_f32_e32 v4, v76, v138
	v_fmac_f32_e32 v5, v80, v138
	v_fmac_f32_e32 v12, v84, v138
	v_fmac_f32_e32 v13, v88, v138
	v_fmac_f32_e32 v22, v92, v138
	v_fmac_f32_e32 v4, v77, v139
	v_fmac_f32_e32 v5, v81, v139
	v_fmac_f32_e32 v12, v85, v139
	v_fmac_f32_e32 v13, v89, v139
	v_fmac_f32_e32 v22, v93, v139
	ds_read_b128 v[74:77], v23 offset:48
	ds_read_b128 v[78:81], v23 offset:4144
	ds_read_b128 v[82:85], v23 offset:8240
	ds_read_b128 v[86:89], v23 offset:12336
	ds_read_b128 v[90:93], v23 offset:16432
	s_waitcnt vmcnt(52) lgkmcnt(5)
	v_fmac_f32_e32 v4, v28, v140
	v_fmac_f32_e32 v5, v32, v140
	v_fmac_f32_e32 v12, v36, v140
	v_fmac_f32_e32 v13, v40, v140
	v_fmac_f32_e32 v22, v44, v140
	v_fmac_f32_e32 v4, v29, v141
	v_fmac_f32_e32 v5, v33, v141
	v_fmac_f32_e32 v12, v37, v141
	v_fmac_f32_e32 v13, v41, v141
	v_fmac_f32_e32 v22, v45, v141
	v_fmac_f32_e32 v4, v30, v142
	v_fmac_f32_e32 v5, v34, v142
	v_fmac_f32_e32 v12, v38, v142
	v_fmac_f32_e32 v13, v42, v142
	v_fmac_f32_e32 v22, v46, v142
	v_fmac_f32_e32 v4, v31, v143
	v_fmac_f32_e32 v5, v35, v143
	v_fmac_f32_e32 v12, v39, v143
	v_fmac_f32_e32 v13, v43, v143
	v_fmac_f32_e32 v22, v47, v143
	ds_read_b128 v[28:31], v23 offset:64
	ds_read_b128 v[32:35], v23 offset:4160
	ds_read_b128 v[36:39], v23 offset:8256
	ds_read_b128 v[40:43], v23 offset:12352
	ds_read_b128 v[44:47], v23 offset:16448
	s_waitcnt vmcnt(48) lgkmcnt(5)
	v_fmac_f32_e32 v4, v74, v144
	v_fmac_f32_e32 v5, v78, v144
	v_fmac_f32_e32 v12, v82, v144
	v_fmac_f32_e32 v13, v86, v144
	v_fmac_f32_e32 v22, v90, v144
	v_fmac_f32_e32 v4, v75, v145
	v_fmac_f32_e32 v5, v79, v145
	v_fmac_f32_e32 v12, v83, v145
	v_fmac_f32_e32 v13, v87, v145
	v_fmac_f32_e32 v22, v91, v145
	v_fmac_f32_e32 v4, v76, v146
	v_fmac_f32_e32 v5, v80, v146
	v_fmac_f32_e32 v12, v84, v146
	v_fmac_f32_e32 v13, v88, v146
	v_fmac_f32_e32 v22, v92, v146
	v_fmac_f32_e32 v4, v77, v147
	v_fmac_f32_e32 v5, v81, v147
	v_fmac_f32_e32 v12, v85, v147
	v_fmac_f32_e32 v13, v89, v147
	v_fmac_f32_e32 v22, v93, v147
	ds_read_b128 v[74:77], v23 offset:80
	ds_read_b128 v[78:81], v23 offset:4176
	ds_read_b128 v[82:85], v23 offset:8272
	ds_read_b128 v[86:89], v23 offset:12368
	ds_read_b128 v[90:93], v23 offset:16464
	s_waitcnt vmcnt(44) lgkmcnt(5)
	v_fmac_f32_e32 v4, v28, v148
	v_fmac_f32_e32 v5, v32, v148
	v_fmac_f32_e32 v12, v36, v148
	v_fmac_f32_e32 v13, v40, v148
	v_fmac_f32_e32 v22, v44, v148
	v_fmac_f32_e32 v4, v29, v149
	v_fmac_f32_e32 v5, v33, v149
	v_fmac_f32_e32 v12, v37, v149
	v_fmac_f32_e32 v13, v41, v149
	v_fmac_f32_e32 v22, v45, v149
	v_fmac_f32_e32 v4, v30, v150
	v_fmac_f32_e32 v5, v34, v150
	v_fmac_f32_e32 v12, v38, v150
	v_fmac_f32_e32 v13, v42, v150
	v_fmac_f32_e32 v22, v46, v150
	v_fmac_f32_e32 v4, v31, v151
	v_fmac_f32_e32 v5, v35, v151
	v_fmac_f32_e32 v12, v39, v151
	v_fmac_f32_e32 v13, v43, v151
	v_fmac_f32_e32 v22, v47, v151
	ds_read_b128 v[28:31], v23 offset:96
	ds_read_b128 v[32:35], v23 offset:4192
	ds_read_b128 v[36:39], v23 offset:8288
	ds_read_b128 v[40:43], v23 offset:12384
	ds_read_b128 v[44:47], v23 offset:16480
	s_waitcnt vmcnt(40) lgkmcnt(5)
	v_fmac_f32_e32 v4, v74, v152
	v_fmac_f32_e32 v5, v78, v152
	v_fmac_f32_e32 v12, v82, v152
	v_fmac_f32_e32 v13, v86, v152
	v_fmac_f32_e32 v22, v90, v152
	v_fmac_f32_e32 v4, v75, v153
	v_fmac_f32_e32 v5, v79, v153
	v_fmac_f32_e32 v12, v83, v153
	v_fmac_f32_e32 v13, v87, v153
	v_fmac_f32_e32 v22, v91, v153
	v_fmac_f32_e32 v4, v76, v154
	v_fmac_f32_e32 v5, v80, v154
	v_fmac_f32_e32 v12, v84, v154
	v_fmac_f32_e32 v13, v88, v154
	v_fmac_f32_e32 v22, v92, v154
	v_fmac_f32_e32 v4, v77, v155
	v_fmac_f32_e32 v5, v81, v155
	v_fmac_f32_e32 v12, v85, v155
	v_fmac_f32_e32 v13, v89, v155
	v_fmac_f32_e32 v22, v93, v155
	ds_read_b128 v[74:77], v23 offset:112
	ds_read_b128 v[78:81], v23 offset:4208
	ds_read_b128 v[82:85], v23 offset:8304
	ds_read_b128 v[86:89], v23 offset:12400
	ds_read_b128 v[90:93], v23 offset:16496
	s_waitcnt vmcnt(36) lgkmcnt(5)
	v_fmac_f32_e32 v4, v28, v156
	v_fmac_f32_e32 v5, v32, v156
	v_fmac_f32_e32 v12, v36, v156
	v_fmac_f32_e32 v13, v40, v156
	v_fmac_f32_e32 v22, v44, v156
	v_fmac_f32_e32 v4, v29, v157
	v_fmac_f32_e32 v5, v33, v157
	v_fmac_f32_e32 v12, v37, v157
	v_fmac_f32_e32 v13, v41, v157
	v_fmac_f32_e32 v22, v45, v157
	v_fmac_f32_e32 v4, v30, v158
	v_fmac_f32_e32 v5, v34, v158
	v_fmac_f32_e32 v12, v38, v158
	v_fmac_f32_e32 v13, v42, v158
	v_fmac_f32_e32 v22, v46, v158
	v_fmac_f32_e32 v4, v31, v159
	v_fmac_f32_e32 v5, v35, v159
	v_fmac_f32_e32 v12, v39, v159
	v_fmac_f32_e32 v13, v43, v159
	v_fmac_f32_e32 v22, v47, v159
	ds_read_b128 v[28:31], v23 offset:128
	ds_read_b128 v[32:35], v23 offset:4224
	ds_read_b128 v[36:39], v23 offset:8320
	ds_read_b128 v[40:43], v23 offset:12416
	ds_read_b128 v[44:47], v23 offset:16512
	s_waitcnt vmcnt(32) lgkmcnt(5)
	v_fmac_f32_e32 v4, v74, v160
	v_fmac_f32_e32 v5, v78, v160
	v_fmac_f32_e32 v12, v82, v160
	v_fmac_f32_e32 v13, v86, v160
	v_fmac_f32_e32 v22, v90, v160
	v_fmac_f32_e32 v4, v75, v161
	v_fmac_f32_e32 v5, v79, v161
	v_fmac_f32_e32 v12, v83, v161
	v_fmac_f32_e32 v13, v87, v161
	v_fmac_f32_e32 v22, v91, v161
	v_fmac_f32_e32 v4, v76, v162
	v_fmac_f32_e32 v5, v80, v162
	v_fmac_f32_e32 v12, v84, v162
	v_fmac_f32_e32 v13, v88, v162
	v_fmac_f32_e32 v22, v92, v162
	v_fmac_f32_e32 v4, v77, v163
	v_fmac_f32_e32 v5, v81, v163
	v_fmac_f32_e32 v12, v85, v163
	v_fmac_f32_e32 v13, v89, v163
	v_fmac_f32_e32 v22, v93, v163
	ds_read_b128 v[74:77], v23 offset:144
	ds_read_b128 v[78:81], v23 offset:4240
	ds_read_b128 v[82:85], v23 offset:8336
	ds_read_b128 v[86:89], v23 offset:12432
	ds_read_b128 v[90:93], v23 offset:16528
	s_waitcnt vmcnt(28) lgkmcnt(5)
	v_fmac_f32_e32 v4, v28, v164
	v_fmac_f32_e32 v5, v32, v164
	v_fmac_f32_e32 v12, v36, v164
	v_fmac_f32_e32 v13, v40, v164
	v_fmac_f32_e32 v22, v44, v164
	v_fmac_f32_e32 v4, v29, v165
	v_fmac_f32_e32 v5, v33, v165
	v_fmac_f32_e32 v12, v37, v165
	v_fmac_f32_e32 v13, v41, v165
	v_fmac_f32_e32 v22, v45, v165
	v_fmac_f32_e32 v4, v30, v166
	v_fmac_f32_e32 v5, v34, v166
	v_fmac_f32_e32 v12, v38, v166
	v_fmac_f32_e32 v13, v42, v166
	v_fmac_f32_e32 v22, v46, v166
	v_fmac_f32_e32 v4, v31, v167
	v_fmac_f32_e32 v5, v35, v167
	v_fmac_f32_e32 v12, v39, v167
	v_fmac_f32_e32 v13, v43, v167
	v_fmac_f32_e32 v22, v47, v167
	ds_read_b128 v[28:31], v23 offset:160
	ds_read_b128 v[32:35], v23 offset:4256
	ds_read_b128 v[36:39], v23 offset:8352
	ds_read_b128 v[40:43], v23 offset:12448
	ds_read_b128 v[44:47], v23 offset:16544
	s_waitcnt vmcnt(24) lgkmcnt(5)
	v_fmac_f32_e32 v4, v74, v168
	v_fmac_f32_e32 v5, v78, v168
	v_fmac_f32_e32 v12, v82, v168
	v_fmac_f32_e32 v13, v86, v168
	v_fmac_f32_e32 v22, v90, v168
	v_fmac_f32_e32 v4, v75, v169
	v_fmac_f32_e32 v5, v79, v169
	v_fmac_f32_e32 v12, v83, v169
	v_fmac_f32_e32 v13, v87, v169
	v_fmac_f32_e32 v22, v91, v169
	v_fmac_f32_e32 v4, v76, v170
	v_fmac_f32_e32 v5, v80, v170
	v_fmac_f32_e32 v12, v84, v170
	v_fmac_f32_e32 v13, v88, v170
	v_fmac_f32_e32 v22, v92, v170
	v_fmac_f32_e32 v4, v77, v171
	v_fmac_f32_e32 v5, v81, v171
	v_fmac_f32_e32 v12, v85, v171
	v_fmac_f32_e32 v13, v89, v171
	v_fmac_f32_e32 v22, v93, v171
	ds_read_b128 v[74:77], v23 offset:176
	ds_read_b128 v[78:81], v23 offset:4272
	ds_read_b128 v[82:85], v23 offset:8368
	ds_read_b128 v[86:89], v23 offset:12464
	ds_read_b128 v[90:93], v23 offset:16560
	s_waitcnt vmcnt(20) lgkmcnt(5)
	v_fmac_f32_e32 v4, v28, v172
	v_fmac_f32_e32 v5, v32, v172
	v_fmac_f32_e32 v12, v36, v172
	v_fmac_f32_e32 v13, v40, v172
	v_fmac_f32_e32 v22, v44, v172
	v_fmac_f32_e32 v4, v29, v173
	v_fmac_f32_e32 v5, v33, v173
	v_fmac_f32_e32 v12, v37, v173
	v_fmac_f32_e32 v13, v41, v173
	v_fmac_f32_e32 v22, v45, v173
	v_fmac_f32_e32 v4, v30, v174
	v_fmac_f32_e32 v5, v34, v174
	v_fmac_f32_e32 v12, v38, v174
	v_fmac_f32_e32 v13, v42, v174
	v_fmac_f32_e32 v22, v46, v174
	v_fmac_f32_e32 v4, v31, v175
	v_fmac_f32_e32 v5, v35, v175
	v_fmac_f32_e32 v12, v39, v175
	v_fmac_f32_e32 v13, v43, v175
	v_fmac_f32_e32 v22, v47, v175
	ds_read_b128 v[28:31], v23 offset:192
	ds_read_b128 v[32:35], v23 offset:4288
	ds_read_b128 v[36:39], v23 offset:8384
	ds_read_b128 v[40:43], v23 offset:12480
	ds_read_b128 v[44:47], v23 offset:16576
	s_waitcnt vmcnt(16) lgkmcnt(5)
	v_fmac_f32_e32 v4, v74, v176
	v_fmac_f32_e32 v5, v78, v176
	v_fmac_f32_e32 v12, v82, v176
	v_fmac_f32_e32 v13, v86, v176
	v_fmac_f32_e32 v22, v90, v176
	v_fmac_f32_e32 v4, v75, v177
	v_fmac_f32_e32 v5, v79, v177
	v_fmac_f32_e32 v12, v83, v177
	v_fmac_f32_e32 v13, v87, v177
	v_fmac_f32_e32 v22, v91, v177
	v_fmac_f32_e32 v4, v76, v178
	v_fmac_f32_e32 v5, v80, v178
	v_fmac_f32_e32 v12, v84, v178
	v_fmac_f32_e32 v13, v88, v178
	v_fmac_f32_e32 v22, v92, v178
	v_fmac_f32_e32 v4, v77, v179
	v_fmac_f32_e32 v5, v81, v179
	v_fmac_f32_e32 v12, v85, v179
	v_fmac_f32_e32 v13, v89, v179
	v_fmac_f32_e32 v22, v93, v179
	ds_read_b128 v[74:77], v23 offset:208
	ds_read_b128 v[78:81], v23 offset:4304
	ds_read_b128 v[82:85], v23 offset:8400
	ds_read_b128 v[86:89], v23 offset:12496
	ds_read_b128 v[90:93], v23 offset:16592
	s_waitcnt vmcnt(12) lgkmcnt(5)
	v_fmac_f32_e32 v4, v28, v180
	v_fmac_f32_e32 v5, v32, v180
	v_fmac_f32_e32 v12, v36, v180
	v_fmac_f32_e32 v13, v40, v180
	v_fmac_f32_e32 v22, v44, v180
	v_fmac_f32_e32 v4, v29, v181
	v_fmac_f32_e32 v5, v33, v181
	v_fmac_f32_e32 v12, v37, v181
	v_fmac_f32_e32 v13, v41, v181
	v_fmac_f32_e32 v22, v45, v181
	v_fmac_f32_e32 v4, v30, v182
	v_fmac_f32_e32 v5, v34, v182
	v_fmac_f32_e32 v12, v38, v182
	v_fmac_f32_e32 v13, v42, v182
	v_fmac_f32_e32 v22, v46, v182
	v_fmac_f32_e32 v4, v31, v183
	v_fmac_f32_e32 v5, v35, v183
	v_fmac_f32_e32 v12, v39, v183
	v_fmac_f32_e32 v13, v43, v183
	v_fmac_f32_e32 v22, v47, v183
	ds_read_b128 v[28:31], v23 offset:224
	ds_read_b128 v[32:35], v23 offset:4320
	ds_read_b128 v[36:39], v23 offset:8416
	ds_read_b128 v[40:43], v23 offset:12512
	ds_read_b128 v[44:47], v23 offset:16608
	s_waitcnt vmcnt(8) lgkmcnt(5)
	v_fmac_f32_e32 v4, v74, v184
	v_fmac_f32_e32 v5, v78, v184
	v_fmac_f32_e32 v12, v82, v184
	v_fmac_f32_e32 v13, v86, v184
	v_fmac_f32_e32 v22, v90, v184
	v_fmac_f32_e32 v4, v75, v185
	v_fmac_f32_e32 v5, v79, v185
	v_fmac_f32_e32 v12, v83, v185
	v_fmac_f32_e32 v13, v87, v185
	v_fmac_f32_e32 v22, v91, v185
	v_fmac_f32_e32 v4, v76, v186
	v_fmac_f32_e32 v5, v80, v186
	v_fmac_f32_e32 v12, v84, v186
	v_fmac_f32_e32 v13, v88, v186
	v_fmac_f32_e32 v22, v92, v186
	v_fmac_f32_e32 v4, v77, v187
	v_fmac_f32_e32 v5, v81, v187
	v_fmac_f32_e32 v12, v85, v187
	v_fmac_f32_e32 v13, v89, v187
	v_fmac_f32_e32 v22, v93, v187
	ds_read_b128 v[74:77], v23 offset:240
	ds_read_b128 v[78:81], v23 offset:4336
	ds_read_b128 v[82:85], v23 offset:8432
	ds_read_b128 v[86:89], v23 offset:12528
	ds_read_b128 v[90:93], v23 offset:16624
	s_waitcnt vmcnt(4) lgkmcnt(5)
	v_fmac_f32_e32 v4, v28, v192
	v_fmac_f32_e32 v5, v32, v192
	v_fmac_f32_e32 v12, v36, v192
	v_fmac_f32_e32 v13, v40, v192
	v_fmac_f32_e32 v22, v44, v192
	v_fmac_f32_e32 v4, v29, v193
	v_fmac_f32_e32 v5, v33, v193
	v_fmac_f32_e32 v12, v37, v193
	v_fmac_f32_e32 v13, v41, v193
	v_fmac_f32_e32 v22, v45, v193
	v_fmac_f32_e32 v4, v30, v194
	v_fmac_f32_e32 v5, v34, v194
	v_fmac_f32_e32 v12, v38, v194
	v_fmac_f32_e32 v13, v42, v194
	v_fmac_f32_e32 v22, v46, v194
	v_fmac_f32_e32 v4, v31, v195
	v_fmac_f32_e32 v5, v35, v195
	v_fmac_f32_e32 v12, v39, v195
	v_fmac_f32_e32 v13, v43, v195
	v_fmac_f32_e32 v22, v47, v195
	s_waitcnt vmcnt(0) lgkmcnt(0)
	v_fmac_f32_e32 v4, v74, v196
	v_fmac_f32_e32 v5, v78, v196
	v_fmac_f32_e32 v12, v82, v196
	v_fmac_f32_e32 v13, v86, v196
	v_fmac_f32_e32 v22, v90, v196
	v_fmac_f32_e32 v4, v75, v197
	v_fmac_f32_e32 v5, v79, v197
	v_fmac_f32_e32 v12, v83, v197
	v_fmac_f32_e32 v13, v87, v197
	v_fmac_f32_e32 v22, v91, v197
	v_fmac_f32_e32 v4, v76, v198
	v_fmac_f32_e32 v5, v80, v198
	v_fmac_f32_e32 v12, v84, v198
	v_fmac_f32_e32 v13, v88, v198
	v_fmac_f32_e32 v22, v92, v198
	v_fmac_f32_e32 v4, v77, v199
	v_fmac_f32_e32 v5, v81, v199
	v_fmac_f32_e32 v12, v85, v199
	v_fmac_f32_e32 v13, v89, v199
	v_fmac_f32_e32 v22, v93, v199
	v_mov_b32_e32 v2, v11
	v_mad_u64_u32 v[2:3], s[6:7], v0, 20, v[2:3]
	v_add_u32_e32 v3, 0x5000, v2
	s_movk_i32 s6, 0xa0
	ds_write2_b32 v3, v4, v5 offset1:1
	v_add_u32_e32 v3, 0x5008, v2
	v_cmp_gt_i32_e32 vcc, s6, v0
	ds_write2_b32 v3, v12, v13 offset1:1
	ds_write_b32 v2, v22 offset:20496
	s_waitcnt lgkmcnt(0)
	s_barrier
	s_and_saveexec_b64 s[6:7], vcc
	s_cbranch_execz .LBB0_23
	s_lshl_b32 s8, s39, 5
	v_or_b32_e32 v2, s8, v1
	v_ashrrev_i32_e32 v3, 31, v2
	v_lshl_add_u64 v[2:3], v[2:3], 2, s[50:51]
	global_load_dword v21, v[2:3], off
	v_lshlrev_b32_e32 v0, 2, v10
	v_mul_u32_u24_e32 v2, 20, v1
	s_movk_i32 s9, 0x1800
	v_mul_lo_u32 v3, v10, s9
	v_add3_u32 v0, 0, v0, v2
	v_add_u32_e32 v2, s8, v3
	v_add_u32_e32 v3, 0x5000, v0
	v_add_u32_e32 v4, 0x5400, v0
	v_add_u32_e32 v22, 0x5e00, v0
	v_add_u32_e32 v28, 0x6400, v0
	v_add_u32_e32 v30, 0x6800, v0
	v_add_u32_e32 v32, 0x6e00, v0
	v_add_u32_e32 v34, 0x7200, v0
	v_add_u32_e32 v10, 0x5a00, v0
	v_or_b32_e32 v0, v2, v1
	ds_read2_b32 v[2:3], v3 offset1:160
	ds_read2_b32 v[4:5], v4 offset0:64 offset1:224
	ds_read2_b32 v[12:13], v10 offset1:160
	ds_read2_b32 v[22:23], v22 offset0:64 offset1:224
	ds_read2_b32 v[28:29], v28 offset1:160
	ds_read2_b32 v[30:31], v30 offset0:64 offset1:224
	ds_read2_b32 v[32:33], v32 offset1:160
	ds_read2_b32 v[34:35], v34 offset0:64 offset1:224
	v_ashrrev_i32_e32 v1, 31, v0
	v_lshl_add_u64 v[0:1], v[0:1], 2, s[14:15]
	s_waitcnt vmcnt(0) lgkmcnt(7)
	v_add_f32_e32 v2, v21, v2
	v_add_f32_e32 v2, v2, v3
	s_waitcnt lgkmcnt(6)
	v_add_f32_e32 v2, v2, v4
	v_add_f32_e32 v2, v2, v5
	s_waitcnt lgkmcnt(5)
	v_add_f32_e32 v2, v2, v12
	v_add_f32_e32 v2, v2, v13
	s_waitcnt lgkmcnt(4)
	v_add_f32_e32 v2, v2, v22
	v_add_f32_e32 v2, v2, v23
	s_waitcnt lgkmcnt(3)
	v_add_f32_e32 v2, v2, v28
	v_add_f32_e32 v2, v2, v29
	s_waitcnt lgkmcnt(2)
	v_add_f32_e32 v2, v2, v30
	v_add_f32_e32 v2, v2, v31
	s_waitcnt lgkmcnt(1)
	v_add_f32_e32 v2, v2, v32
	v_add_f32_e32 v2, v2, v33
	s_waitcnt lgkmcnt(0)
	v_add_f32_e32 v2, v2, v34
	v_add_f32_e32 v2, v2, v35
	global_store_dword v[0:1], v2, off
	s_branch .LBB0_23
